# phase_tail low-rank section: all 20 operand loads issued up front (second half into fresh registers) instead of two serial load-wait-MFMA rounds
# speedup vs baseline: 1.0139x; 1.0066x over previous
.LBB0_225:
	v_lshrrev_b32_e32 v98, 8, v0
	v_bfe_u32 v99, v0, 4, 2
	v_lshl_add_u32 v98, v98, 4, v99
	v_lshlrev_b32_e32 v98, 10, v98
	v_bfe_u32 v99, v0, 6, 2
	v_lshlrev_b32_e32 v99, 8, v99
	v_and_b32_e32 v116, 15, v0
	v_lshl_add_u32 v99, v116, 4, v99
	v_add_u32_e32 v98, v98, v99
	s_add_u32 s4, s60, 0x1000
	s_addc_u32 s5, s61, 0
	s_add_u32 s6, s60, 0x2000
	s_addc_u32 s7, s61, 0
	s_add_u32 s8, s60, 0x3000
	s_addc_u32 s9, s61, 0
	global_load_dwordx4 v[100:103], v98, s[60:61]
	global_load_dwordx4 v[104:107], v98, s[4:5]
	global_load_dwordx4 v[108:111], v98, s[6:7]
	global_load_dwordx4 v[112:115], v98, s[8:9]
	v_lshrrev_b32_e32 v99, 6, v0
	v_lshlrev_b32_e32 v99, 8, v99
	v_lshl_add_u32 v99, v116, 4, v99
	global_load_dwordx4 v[116:119], v99, s[62:63]
	s_mul_i32 s4, s19, 48
	v_or_b32_e32 v40, s4, v34
	v_ashrrev_i32_e32 v41, 31, v40
	v_lshlrev_b64 v[40:41], 11, v[40:41]
	v_lshl_add_u64 v[88:89], v[18:19], 0, v[40:41]
	v_add_co_u32_e32 v90, vcc, 0x8000, v88
	global_load_dwordx4 v[40:43], v[88:89], off
	global_load_dwordx4 v[44:47], v[20:21], off
	global_load_dwordx4 v[48:51], v[22:23], off
	v_addc_co_u32_e32 v91, vcc, 0, v89, vcc
	v_add_co_u32_e32 v96, vcc, 0x10000, v88
	global_load_dwordx4 v[52:55], v[90:91], off
	global_load_dwordx4 v[56:59], v[20:21], off offset:64
	global_load_dwordx4 v[60:63], v[88:89], off offset:64
	v_addc_co_u32_e32 v97, vcc, 0, v89, vcc
	global_load_dwordx4 v[80:83], v[96:97], off
	global_load_dwordx4 v[84:87], v[96:97], off offset:64
	global_load_dwordx4 v[68:71], v[26:27], off
	global_load_dwordx4 v[72:75], v[90:91], off offset:64
	global_load_dwordx4 v[120:123], v[88:89], off offset:128
	global_load_dwordx4 v[124:127], v[20:21], off offset:128
	global_load_dwordx4 v[128:131], v[20:21], off offset:192
	global_load_dwordx4 v[132:135], v[88:89], off offset:192
	global_load_dwordx4 v[136:139], v[28:29], off
	global_load_dwordx4 v[140:143], v[30:31], off
	global_load_dwordx4 v[144:147], v[90:91], off offset:128
	global_load_dwordx4 v[148:151], v[90:91], off offset:192
	global_load_dwordx4 v[152:155], v[96:97], off offset:128
	global_load_dwordx4 v[156:159], v[96:97], off offset:192
	s_waitcnt vmcnt(18)
	v_mfma_f32_16x16x32_bf16 v[64:67], v[40:43], v[44:47], 0
	s_waitcnt vmcnt(17)
	v_mfma_f32_16x16x32_bf16 v[40:43], v[40:43], v[48:51], 0
	s_waitcnt vmcnt(16)
	v_mfma_f32_16x16x32_bf16 v[76:79], v[52:55], v[44:47], 0
	s_waitcnt vmcnt(13)
	v_mfma_f32_16x16x32_bf16 v[44:47], v[80:83], v[44:47], 0
	v_mfma_f32_16x16x32_bf16 v[64:67], v[60:63], v[56:59], v[64:67]
	s_waitcnt vmcnt(11)
	v_mfma_f32_16x16x32_bf16 v[40:43], v[60:63], v[68:71], v[40:43]
	s_waitcnt vmcnt(10)
	v_mfma_f32_16x16x32_bf16 v[60:63], v[72:75], v[56:59], v[76:79]
	v_mfma_f32_16x16x32_bf16 v[44:47], v[84:87], v[56:59], v[44:47]
	v_mfma_f32_16x16x32_bf16 v[52:55], v[52:55], v[48:51], 0
	v_mfma_f32_16x16x32_bf16 v[48:51], v[80:83], v[48:51], 0
	v_mfma_f32_16x16x32_bf16 v[52:55], v[72:75], v[68:71], v[52:55]
	v_mfma_f32_16x16x32_bf16 v[48:51], v[84:87], v[68:71], v[48:51]
	s_waitcnt vmcnt(8)
	v_mfma_f32_16x16x32_bf16 v[64:67], v[120:123], v[124:127], v[64:67]
	s_waitcnt vmcnt(5)
	v_mfma_f32_16x16x32_bf16 v[40:43], v[120:123], v[136:139], v[40:43]
	v_mfma_f32_16x16x32_bf16 v[64:67], v[132:135], v[128:131], v[64:67]
	s_waitcnt vmcnt(4)
	v_mfma_f32_16x16x32_bf16 v[40:43], v[132:135], v[140:143], v[40:43]
	s_waitcnt vmcnt(3)
	v_mfma_f32_16x16x32_bf16 v[60:63], v[144:147], v[124:127], v[60:63]
	v_mfma_f32_16x16x32_bf16 v[52:55], v[144:147], v[136:139], v[52:55]
	s_waitcnt vmcnt(1)
	v_mfma_f32_16x16x32_bf16 v[44:47], v[152:155], v[124:127], v[44:47]
	v_add_u32_e32 v68, v35, v1
	v_mfma_f32_16x16x32_bf16 v[48:51], v[152:155], v[136:139], v[48:51]
	v_mfma_f32_16x16x32_bf16 v[60:63], v[148:151], v[128:131], v[60:63]
	v_mfma_f32_16x16x32_bf16 v[52:55], v[148:151], v[140:143], v[52:55]
	s_waitcnt vmcnt(0)
	v_mfma_f32_16x16x32_bf16 v[44:47], v[156:159], v[128:131], v[44:47]
	v_mfma_f32_16x16x32_bf16 v[48:51], v[156:159], v[140:143], v[48:51]
	ds_write2_b32 v68, v64, v40 offset1:16
	ds_write2_b32 v68, v65, v41 offset0:33 offset1:49
	ds_write2_b32 v68, v66, v42 offset0:66 offset1:82
	ds_write2_b32 v68, v67, v43 offset0:99 offset1:115
	s_nop 0
	ds_write2_b32 v37, v60, v52 offset1:16
	ds_write2_b32 v37, v61, v53 offset0:33 offset1:49
	ds_write2_b32 v37, v62, v54 offset0:66 offset1:82
	ds_write2_b32 v37, v63, v55 offset0:99 offset1:115
	ds_write2_b32 v38, v44, v48 offset1:16
	ds_write2_b32 v38, v45, v49 offset0:33 offset1:49
	ds_write2_b32 v38, v46, v50 offset0:66 offset1:82
	ds_write2_b32 v38, v47, v51 offset0:99 offset1:115
	s_waitcnt lgkmcnt(0)
	s_barrier
	s_and_saveexec_b64 s[4:5], s[0:1]
	s_cbranch_execz .LBB0_228
	s_mov_b64 s[6:7], 0
	v_mov_b32_e32 v40, v0
